# LRU stores rows 2,3: address = previous row address + stride (drop 16 quarter-rate v_mad_u64 and 28 more VALU per chunk)
# baseline (speedup 1.0000x reference)
; __device__ __forceinline__ bf16_t f2bf(float f) { unsigned u = __float_as_uint(f); u += 0x7FFFu + ((u >> 16) & 1u); return (bf16_t)(u >> 16); }
; __device__ __forceinline__ float bf2f(bf16_t b) { return __uint_as_float(((unsigned)b) << 16); }
; __device__ void lru_fused_phase(const int bid, const int nblk, bf16_t* __restrict__ U, bf16_t* __restrict__ HF, const bf16_t* __restrict__ Wg, const float* __restrict__ cw, const float* __restrict__ cb, ...
;     ...
; #pragma unroll
;                     for (int j = 0; j < 4; ++j) {
;                         const float hv = hl[j] + pp[j] * carry;
;                         if (e == 0) HF[(grow + j) * DRNN + ch] = f2bf(hv);
;                         else U[(grow + j) * (2 * DRNN) + ch] = f2bf((bf2f(hfv[j]) + hv) * bf2f(gtv[j]));
;                     }
.LBB0_137:
	v_lshl_add_u64 v[40:41], v[40:41], 0, s[36:37]
	v_cvt_pk_bf16_f32 v36, v108, v108
	s_and_b64 vcc, exec, s[8:9]
	v_fmac_f32_e32 v43, v39, v37
	global_store_short v[40:41], v36, off
	s_cbranch_vccnz .LBB0_139
	s_waitcnt vmcnt(4)
	v_lshlrev_b32_e32 v36, 16, v84
	v_add_f32_e32 v36, v43, v36
	s_waitcnt vmcnt(3)
	v_lshlrev_b32_e32 v37, 16, v91
	v_mul_f32_e32 v43, v36, v37
	s_mov_b32 s38, 32
	s_mov_b64 s[2:3], 0x3c00
	s_mov_b64 s[14:15], 0x1400
	s_mov_b64 s[36:37], s[46:47]
	s_branch .LBB0_140

; __device__ __forceinline__ bf16_t f2bf(float f) { unsigned u = __float_as_uint(f); u += 0x7FFFu + ((u >> 16) & 1u); return (bf16_t)(u >> 16); }
; __device__ __forceinline__ float bf2f(bf16_t b) { return __uint_as_float(((unsigned)b) << 16); }
; __device__ void lru_fused_phase(const int bid, const int nblk, bf16_t* __restrict__ U, bf16_t* __restrict__ HF, const bf16_t* __restrict__ Wg, const float* __restrict__ cw, const float* __restrict__ cb, ...
;     ...
;                     const long grow = rowb + 64 * k + 16 * rt + 4 * fq;
;                     unsigned short hfv[4], gtv[4];
;                     if (e == 1) {
; #pragma unroll
;                         for (int j = 0; j < 4; ++j) { hfv[j] = HF[(grow + j) * DRNN + ch]; gtv[j] = U[(grow + j) * (2 * DRNN) + ch]; }
;                     }
;     ...
; #pragma unroll
;                     for (int j = 0; j < 4; ++j) {
;                         const float hv = hl[j] + pp[j] * carry;
;                         if (e == 0) HF[(grow + j) * DRNN + ch] = f2bf(hv);
;                         else U[(grow + j) * (2 * DRNN) + ch] = f2bf((bf2f(hfv[j]) + hv) * bf2f(gtv[j]));
;                     }
.LBB0_140:
	v_lshl_add_u64 v[36:37], v[40:41], 0, s[14:15]
	v_cvt_pk_bf16_f32 v38, v43, v43
	s_and_b64 vcc, exec, s[10:11]
	v_or_b32_e32 v107, s38, v68
	global_store_short v[36:37], v38, off
	s_cbranch_vccnz .LBB0_142
	v_mad_u64_u32 v[36:37], s[2:3], v107, s77, v[66:67]
	v_mov_b32_e32 v38, v37
	v_mad_u64_u32 v[38:39], s[2:3], v69, s77, v[38:39]
	v_mov_b32_e32 v37, v38
	v_mad_u64_u32 v[38:39], s[2:3], v107, s43, v[64:65]
	v_mov_b32_e32 v40, v39
	v_lshl_add_u64 v[42:43], v[36:37], 0, s[50:51]
	global_load_ushort v77, v[36:37], off
	global_load_ushort v79, v[36:37], off offset:2560
	global_load_ushort v81, v[42:43], off offset:2560
	v_mad_u64_u32 v[40:41], s[2:3], v69, s43, v[40:41]
	v_add_co_u32_e32 v36, vcc, s33, v38
	v_mov_b32_e32 v39, v40
	s_nop 0
	v_addc_co_u32_e32 v37, vcc, 0, v40, vcc
	global_load_ushort v78, v[38:39], off
	global_load_ushort v80, v[36:37], off offset:1024
	v_lshl_add_u64 v[36:37], v[42:43], 0, s[50:51]
	v_add_co_u32_e32 v42, vcc, 0x2000, v38
	s_nop 1
	v_addc_co_u32_e32 v43, vcc, 0, v40, vcc
	global_load_ushort v85, v[42:43], off offset:2048
	global_load_ushort v84, v[36:37], off offset:2560
	v_add_co_u32_e32 v36, vcc, 0x3000, v38
	s_nop 1
	v_addc_co_u32_e32 v37, vcc, 0, v40, vcc
	global_load_ushort v91, v[36:37], off offset:3072

; __device__ __forceinline__ bf16_t f2bf(float f) { unsigned u = __float_as_uint(f); u += 0x7FFFu + ((u >> 16) & 1u); return (bf16_t)(u >> 16); }
; __device__ __forceinline__ float bf2f(bf16_t b) { return __uint_as_float(((unsigned)b) << 16); }
; __device__ void lru_fused_phase(const int bid, const int nblk, bf16_t* __restrict__ U, bf16_t* __restrict__ HF, const bf16_t* __restrict__ Wg, const float* __restrict__ cw, const float* __restrict__ cb, ...
;     ...
; #pragma unroll
;                     for (int j = 0; j < 4; ++j) {
;                         const float hv = hl[j] + pp[j] * carry;
;                         if (e == 0) HF[(grow + j) * DRNN + ch] = f2bf(hv);
;                         else U[(grow + j) * (2 * DRNN) + ch] = f2bf((bf2f(hfv[j]) + hv) * bf2f(gtv[j]));
;                     }
.LBB0_160:
	v_lshl_add_u64 v[40:41], v[40:41], 0, s[36:37]
	v_cvt_pk_bf16_f32 v38, v108, v108
	s_and_b64 vcc, exec, s[8:9]
	v_fmac_f32_e32 v43, v39, v37
	global_store_short v[40:41], v38, off
	s_cbranch_vccnz .LBB0_162
	s_waitcnt vmcnt(4)
	v_lshlrev_b32_e32 v36, 16, v84
	v_add_f32_e32 v36, v43, v36
	s_waitcnt vmcnt(3)
	v_lshlrev_b32_e32 v37, 16, v91
	v_mul_f32_e32 v43, v36, v37
	s_mov_b32 s38, 16
	s_mov_b64 s[2:3], 0x3c00
	s_mov_b64 s[14:15], 0x1400
	s_mov_b64 s[36:37], s[46:47]
	s_branch .LBB0_163

; __device__ __forceinline__ bf16_t f2bf(float f) { unsigned u = __float_as_uint(f); u += 0x7FFFu + ((u >> 16) & 1u); return (bf16_t)(u >> 16); }
; __device__ __forceinline__ float bf2f(bf16_t b) { return __uint_as_float(((unsigned)b) << 16); }
; __device__ void lru_fused_phase(const int bid, const int nblk, bf16_t* __restrict__ U, bf16_t* __restrict__ HF, const bf16_t* __restrict__ Wg, const float* __restrict__ cw, const float* __restrict__ cb, ...
;     ...
;                     const long grow = rowb + 64 * k + 16 * rt + 4 * fq;
;                     unsigned short hfv[4], gtv[4];
;                     if (e == 1) {
; #pragma unroll
;                         for (int j = 0; j < 4; ++j) { hfv[j] = HF[(grow + j) * DRNN + ch]; gtv[j] = U[(grow + j) * (2 * DRNN) + ch]; }
;                     }
;     ...
; #pragma unroll
;                     for (int j = 0; j < 4; ++j) {
;                         const float hv = hl[j] + pp[j] * carry;
;                         if (e == 0) HF[(grow + j) * DRNN + ch] = f2bf(hv);
;                         else U[(grow + j) * (2 * DRNN) + ch] = f2bf((bf2f(hfv[j]) + hv) * bf2f(gtv[j]));
;                     }
.LBB0_163:
	v_lshl_add_u64 v[36:37], v[40:41], 0, s[14:15]
	v_cvt_pk_bf16_f32 v40, v43, v43
	s_and_b64 vcc, exec, s[10:11]
	v_or_b32_e32 v107, s38, v68
	global_store_short v[36:37], v40, off
	s_cbranch_vccnz .LBB0_165
	v_mad_u64_u32 v[36:37], s[2:3], v107, s77, v[66:67]
	v_mov_b32_e32 v38, v37
	v_mad_u64_u32 v[38:39], s[2:3], v69, s77, v[38:39]
	v_mov_b32_e32 v37, v38
	v_mad_u64_u32 v[38:39], s[2:3], v107, s43, v[64:65]
	v_mov_b32_e32 v40, v39
	v_lshl_add_u64 v[42:43], v[36:37], 0, s[50:51]
	global_load_ushort v77, v[36:37], off
	global_load_ushort v79, v[36:37], off offset:2560
	global_load_ushort v81, v[42:43], off offset:2560
	v_mad_u64_u32 v[40:41], s[2:3], v69, s43, v[40:41]
	v_add_co_u32_e32 v36, vcc, s33, v38
	v_mov_b32_e32 v39, v40
	s_nop 0
	v_addc_co_u32_e32 v37, vcc, 0, v40, vcc
	global_load_ushort v78, v[38:39], off
	global_load_ushort v80, v[36:37], off offset:1024
	v_lshl_add_u64 v[36:37], v[42:43], 0, s[50:51]
	v_add_co_u32_e32 v42, vcc, 0x2000, v38
	s_nop 1
	v_addc_co_u32_e32 v43, vcc, 0, v40, vcc
	global_load_ushort v85, v[42:43], off offset:2048
	global_load_ushort v84, v[36:37], off offset:2560
	v_add_co_u32_e32 v36, vcc, 0x3000, v38
	s_nop 1
	v_addc_co_u32_e32 v37, vcc, 0, v40, vcc
	global_load_ushort v91, v[36:37], off offset:3072

; __device__ __forceinline__ bf16_t f2bf(float f) { unsigned u = __float_as_uint(f); u += 0x7FFFu + ((u >> 16) & 1u); return (bf16_t)(u >> 16); }
; __device__ __forceinline__ float bf2f(bf16_t b) { return __uint_as_float(((unsigned)b) << 16); }
; __device__ void lru_fused_phase(const int bid, const int nblk, bf16_t* __restrict__ U, bf16_t* __restrict__ HF, const bf16_t* __restrict__ Wg, const float* __restrict__ cw, const float* __restrict__ cb, ...
;     ...
; #pragma unroll
;                     for (int j = 0; j < 4; ++j) {
;                         const float hv = hl[j] + pp[j] * carry;
;                         if (e == 0) HF[(grow + j) * DRNN + ch] = f2bf(hv);
;                         else U[(grow + j) * (2 * DRNN) + ch] = f2bf((bf2f(hfv[j]) + hv) * bf2f(gtv[j]));
;                     }
.LBB0_183:
	v_lshl_add_u64 v[40:41], v[40:41], 0, s[36:37]
	v_cvt_pk_bf16_f32 v38, v108, v108
	s_and_b64 vcc, exec, s[8:9]
	v_fmac_f32_e32 v43, v39, v37
	global_store_short v[40:41], v38, off
	s_cbranch_vccnz .LBB0_185
	s_waitcnt vmcnt(4)
	v_lshlrev_b32_e32 v36, 16, v84
	v_add_f32_e32 v36, v43, v36
	s_waitcnt vmcnt(3)
	v_lshlrev_b32_e32 v37, 16, v91
	v_mul_f32_e32 v43, v36, v37
	s_mov_b32 s38, 0
	s_mov_b64 s[2:3], 0x3c00
	s_mov_b64 s[14:15], 0x1400
	s_mov_b64 s[36:37], s[46:47]
	s_branch .LBB0_186

; __device__ __forceinline__ bf16_t f2bf(float f) { unsigned u = __float_as_uint(f); u += 0x7FFFu + ((u >> 16) & 1u); return (bf16_t)(u >> 16); }
; __device__ __forceinline__ float bf2f(bf16_t b) { return __uint_as_float(((unsigned)b) << 16); }
; __device__ void lru_fused_phase(const int bid, const int nblk, bf16_t* __restrict__ U, bf16_t* __restrict__ HF, const bf16_t* __restrict__ Wg, const float* __restrict__ cw, const float* __restrict__ cb, ...
;     ...
;                     const long grow = rowb + 64 * k + 16 * rt + 4 * fq;
;                     unsigned short hfv[4], gtv[4];
;                     if (e == 1) {
; #pragma unroll
;                         for (int j = 0; j < 4; ++j) { hfv[j] = HF[(grow + j) * DRNN + ch]; gtv[j] = U[(grow + j) * (2 * DRNN) + ch]; }
;                     }
;     ...
; #pragma unroll
;                     for (int j = 0; j < 4; ++j) {
;                         const float hv = hl[j] + pp[j] * carry;
;                         if (e == 0) HF[(grow + j) * DRNN + ch] = f2bf(hv);
;                         else U[(grow + j) * (2 * DRNN) + ch] = f2bf((bf2f(hfv[j]) + hv) * bf2f(gtv[j]));
;                     }
.LBB0_186:
	v_lshl_add_u64 v[36:37], v[40:41], 0, s[14:15]
	v_cvt_pk_bf16_f32 v40, v43, v43
	s_and_b64 vcc, exec, s[10:11]
	v_or_b32_e32 v68, s38, v68
	global_store_short v[36:37], v40, off
	s_cbranch_vccnz .LBB0_188
	v_mad_u64_u32 v[36:37], s[2:3], v68, s77, v[66:67]
	v_mov_b32_e32 v38, v37
	v_mad_u64_u32 v[38:39], s[2:3], v69, s77, v[38:39]
	v_mov_b32_e32 v37, v38
	v_mad_u64_u32 v[38:39], s[2:3], v68, s43, v[64:65]
	v_mov_b32_e32 v40, v39
	v_lshl_add_u64 v[42:43], v[36:37], 0, s[50:51]
	global_load_ushort v77, v[36:37], off
	global_load_ushort v79, v[36:37], off offset:2560
	global_load_ushort v81, v[42:43], off offset:2560
	v_mad_u64_u32 v[40:41], s[2:3], v69, s43, v[40:41]
	v_add_co_u32_e32 v36, vcc, s33, v38
	v_mov_b32_e32 v39, v40
	s_nop 0
	v_addc_co_u32_e32 v37, vcc, 0, v40, vcc
	global_load_ushort v78, v[38:39], off
	global_load_ushort v80, v[36:37], off offset:1024
	v_lshl_add_u64 v[36:37], v[42:43], 0, s[50:51]
	v_add_co_u32_e32 v42, vcc, 0x2000, v38
	s_nop 1
	v_addc_co_u32_e32 v43, vcc, 0, v40, vcc
	global_load_ushort v85, v[42:43], off offset:2048
	global_load_ushort v84, v[36:37], off offset:2560
	v_add_co_u32_e32 v36, vcc, 0x3000, v38
	s_nop 1
	v_addc_co_u32_e32 v37, vcc, 0, v40, vcc
	global_load_ushort v91, v[36:37], off offset:3072

; __device__ __forceinline__ bf16_t f2bf(float f) { unsigned u = __float_as_uint(f); u += 0x7FFFu + ((u >> 16) & 1u); return (bf16_t)(u >> 16); }
; __device__ __forceinline__ float bf2f(bf16_t b) { return __uint_as_float(((unsigned)b) << 16); }
; __device__ void lru_fused_phase(const int bid, const int nblk, bf16_t* __restrict__ U, bf16_t* __restrict__ HF, const bf16_t* __restrict__ Wg, const float* __restrict__ cw, const float* __restrict__ cb, ...
;     ...
; #pragma unroll
;                     for (int j = 0; j < 4; ++j) {
;                         const float hv = hl[j] + pp[j] * carry;
;                         if (e == 0) HF[(grow + j) * DRNN + ch] = f2bf(hv);
;                         else U[(grow + j) * (2 * DRNN) + ch] = f2bf((bf2f(hfv[j]) + hv) * bf2f(gtv[j]));
;                     }
.LBB0_206:
	v_lshl_add_u64 v[40:41], v[40:41], 0, s[14:15]
	v_cvt_pk_bf16_f32 v36, v43, v43
	v_fmac_f32_e32 v42, v39, v37
	s_and_b64 vcc, exec, s[8:9]
	s_mov_b64 s[2:3], 0x1e00
	global_store_short v[40:41], v36, off
	s_cbranch_vccnz .LBB0_208
	s_waitcnt vmcnt(4)
	v_lshlrev_b32_e32 v10, 16, v84
	v_add_f32_e32 v10, v42, v10
	s_waitcnt vmcnt(3)
	v_lshlrev_b32_e32 v36, 16, v91
	v_mul_f32_e32 v42, v10, v36
	s_mov_b64 s[2:3], 0x3c00
	s_mov_b64 s[10:11], 0x1400
	s_mov_b64 s[8:9], s[46:47]
	s_branch .LBB0_209

; __device__ __forceinline__ unsigned cvt_pk_bf16(float lo, float hi) { unsigned r; asm volatile("v_cvt_pk_bf16_f32 %0, %1, %2" : "=v"(r) : "v"(lo), "v"(hi)); return r; }
; __device__ __forceinline__ bf16_t f2bf(float f) { unsigned u = __float_as_uint(f); u += 0x7FFFu + ((u >> 16) & 1u); return (bf16_t)(u >> 16); }
; __device__ __forceinline__ float bf2f(bf16_t b) { return __uint_as_float(((unsigned)b) << 16); }
; __device__ __forceinline__ float bflo(unsigned w) { return __uint_as_float(w << 16); }
; __device__ __forceinline__ float bfhi(unsigned w) { return __uint_as_float(w & 0xffff0000u); }
; __device__ void lru_fused_phase(const int bid, const int nblk, bf16_t* __restrict__ U, bf16_t* __restrict__ HF, const bf16_t* __restrict__ Wg, const float* __restrict__ cw, const float* __restrict__ cb, ...
;     ...
; #pragma unroll
;                     for (int j = 0; j < 4; ++j) {
;                         const float hv = hl[j] + pp[j] * carry;
;                         if (e == 0) HF[(grow + j) * DRNN + ch] = f2bf(hv);
;                         else U[(grow + j) * (2 * DRNN) + ch] = f2bf((bf2f(hfv[j]) + hv) * bf2f(gtv[j]));
;                     }
;     ...
;                 if (kk + 1 < 32) {
;                     unsigned char* nb = smem + ((kk + 1) & 1) * (64 * RS);
; #pragma unroll
;                     for (int r = 0; r < 8; ++r) {
;                         const float c0 = wb[0] + w0[0] * bflo(xr[r]) + w1[0] * bflo(xr[r + 1]) + w2[0] * bflo(xr[r + 2]) + w3[0] * bflo(xr[r + 3]);
;                         const float c1 = wb[1] + w0[1] * bfhi(xr[r]) + w1[1] * bfhi(xr[r + 1]) + w2[1] * bfhi(xr[r + 2]) + w3[1] * bfhi(xr[r + 3]);
;                         *(unsigned*)(nb + (8 * wid + r) * RS + lane * 4) = cvt_pk_bf16(c0, c1);
;                     }
.LBB0_209:
	v_lshl_add_u64 v[36:37], v[40:41], 0, s[10:11]
	v_cvt_pk_bf16_f32 v40, v42, v42
	s_andn2_b64 vcc, exec, s[52:53]
	global_store_short v[36:37], v40, off
	s_cbranch_vccnz .LBB0_92
	v_lshlrev_b32_e32 v10, 16, v87
	v_and_b32_e32 v39, 0xffff0000, v87
	v_fma_f32 v10, v48, v10, v56
	v_lshlrev_b32_e32 v36, 16, v88
	v_fma_f32 v39, v49, v39, v57
	v_and_b32_e32 v40, 0xffff0000, v88
	v_fmac_f32_e32 v10, v50, v36
	v_lshlrev_b32_e32 v37, 16, v89
	v_fmac_f32_e32 v39, v51, v40
	v_and_b32_e32 v41, 0xffff0000, v89
	s_bitcmp1_b32 s72, 0
	v_fmac_f32_e32 v10, v52, v37
	v_lshlrev_b32_e32 v38, 16, v90
	v_fmac_f32_e32 v39, v53, v41
	v_and_b32_e32 v42, 0xffff0000, v90
	s_cselect_b32 s2, 0x4400, 0
	v_fmac_f32_e32 v10, v54, v38
	v_fmac_f32_e32 v39, v55, v42
	v_cvt_pk_bf16_f32 v10, v10, v39
	v_add_u32_e32 v39, s2, v75
	ds_write_b32 v39, v10
	v_fma_f32 v10, v48, v36, v56
	v_fmac_f32_e32 v10, v50, v37
	v_fma_f32 v40, v49, v40, v57
	v_fmac_f32_e32 v10, v52, v38
	v_lshlrev_b32_e32 v36, 16, v92
	v_fmac_f32_e32 v40, v51, v41
	v_fmac_f32_e32 v10, v54, v36
	v_fmac_f32_e32 v40, v53, v42
	v_and_b32_e32 v43, 0xffff0000, v92
	v_fmac_f32_e32 v40, v55, v43
	v_cvt_pk_bf16_f32 v10, v10, v40
	ds_write_b32 v39, v10 offset:272
	v_fma_f32 v10, v48, v37, v56
	v_fmac_f32_e32 v10, v50, v38
	v_fma_f32 v40, v49, v41, v57
	v_fmac_f32_e32 v10, v52, v36
	v_lshlrev_b32_e32 v37, 16, v93
	v_fmac_f32_e32 v40, v51, v42
	v_fmac_f32_e32 v10, v54, v37
	v_fmac_f32_e32 v40, v53, v43
	v_and_b32_e32 v41, 0xffff0000, v93
	v_fmac_f32_e32 v40, v55, v41
	v_cvt_pk_bf16_f32 v10, v10, v40
	ds_write_b32 v39, v10 offset:544
	v_fma_f32 v10, v48, v38, v56
	v_fmac_f32_e32 v10, v50, v36
	v_fma_f32 v40, v49, v42, v57
	v_fmac_f32_e32 v10, v52, v37
	v_lshlrev_b32_e32 v38, 16, v94
	v_fmac_f32_e32 v40, v51, v43
	v_fmac_f32_e32 v10, v54, v38
	v_fmac_f32_e32 v40, v53, v41
	v_and_b32_e32 v42, 0xffff0000, v94
	v_fmac_f32_e32 v40, v55, v42
	v_cvt_pk_bf16_f32 v10, v10, v40
	ds_write_b32 v39, v10 offset:816
	v_fma_f32 v10, v48, v36, v56
	v_fmac_f32_e32 v10, v50, v37
	v_fma_f32 v40, v49, v43, v57
	v_fmac_f32_e32 v10, v52, v38
	v_lshlrev_b32_e32 v36, 16, v95
	v_fmac_f32_e32 v40, v51, v41
	v_fmac_f32_e32 v10, v54, v36
	v_fmac_f32_e32 v40, v53, v42
	v_and_b32_e32 v43, 0xffff0000, v95
	v_fmac_f32_e32 v40, v55, v43
	v_cvt_pk_bf16_f32 v10, v10, v40
	ds_write_b32 v39, v10 offset:1088
	v_fma_f32 v10, v48, v37, v56
	v_fmac_f32_e32 v10, v50, v38
	v_fma_f32 v40, v49, v41, v57
	v_fmac_f32_e32 v10, v52, v36
	v_lshlrev_b32_e32 v37, 16, v96
	v_fmac_f32_e32 v40, v51, v42
	v_fmac_f32_e32 v10, v54, v37
	v_fmac_f32_e32 v40, v53, v43
	v_and_b32_e32 v41, 0xffff0000, v96
	v_fmac_f32_e32 v40, v55, v41
	v_cvt_pk_bf16_f32 v10, v10, v40
	ds_write_b32 v39, v10 offset:1360
	v_fma_f32 v10, v48, v38, v56
	v_fmac_f32_e32 v10, v50, v36
	v_fma_f32 v40, v49, v42, v57
	v_fmac_f32_e32 v10, v52, v37
	v_lshlrev_b32_e32 v38, 16, v97
	v_fmac_f32_e32 v40, v51, v43
	v_fmac_f32_e32 v10, v54, v38
	v_fmac_f32_e32 v40, v53, v41
	v_and_b32_e32 v42, 0xffff0000, v97
	v_fmac_f32_e32 v40, v55, v42
	v_cvt_pk_bf16_f32 v10, v10, v40
	ds_write_b32 v39, v10 offset:1632
	v_fma_f32 v10, v48, v36, v56
	v_fmac_f32_e32 v10, v50, v37
	v_fmac_f32_e32 v10, v52, v38
	v_lshlrev_b32_e32 v36, 16, v103
	v_fmac_f32_e32 v10, v54, v36
	v_fma_f32 v36, v49, v43, v57
	v_fmac_f32_e32 v36, v51, v41
	v_fmac_f32_e32 v36, v53, v42
	v_and_b32_e32 v37, 0xffff0000, v103
	v_fmac_f32_e32 v36, v55, v37
	v_cvt_pk_bf16_f32 v10, v10, v36
	ds_write_b32 v39, v10 offset:1904
	s_branch .LBB0_92
